# as previous but instead of no priorities: one static s_setprio 1 for waves 0-3 at kernel entry (all per-phase flips removed)
# baseline (speedup 1.0000x reference)
_Z9hymba_fwd4Args:
	s_load_dwordx8 s[88:95], s[0:1], 0x80
	v_and_b32_e32 v129, 0x3ff, v0
	s_mov_b32 s60, s2
	v_readfirstlane_b32 s2, v129
	s_nop 3
	s_lshr_b32 s98, s2, 6
	s_cmp_ge_u32 s98, 4
	s_cbranch_scc1 .Lmy_prio_done
	s_setprio 1
.Lmy_prio_done:
	s_load_dword s96, s[0:1], 0xa0
	s_mov_b32 s4, 0
	v_writelane_b32 v251, s2, 0
	s_add_u32 s2, s0, 0xa0
	s_addc_u32 s3, s1, 0
	v_writelane_b32 v251, s2, 1
	s_nop 1
	v_writelane_b32 v251, s3, 2
	s_waitcnt lgkmcnt(0)
	s_add_u32 s2, s92, 0x2a0000
	s_addc_u32 s3, s93, 0
	v_writelane_b32 v251, s2, 3
	s_sub_i32 s67, s95, s94
	s_cmp_lt_i32 s67, 2
	v_writelane_b32 v251, s3, 4
	s_cselect_b64 s[2:3], -1, 0
	v_writelane_b32 v251, s4, 5
	v_writelane_b32 v251, s2, 6
	s_and_b64 vcc, exec, s[2:3]
	s_nop 0
	v_writelane_b32 v251, s3, 7
	s_cbranch_vccnz .LBB0_7
	v_cmp_gt_u32_e32 vcc, 4, v129
	s_and_saveexec_b64 s[4:5], vcc
	v_lshl_add_u32 v1, v129, 2, 0
	v_add_u32_e32 v1, 0x27f00, v1
	v_mov_b32_e32 v2, 0
	ds_write_b32 v1, v2
	s_or_b64 exec, exec, s[4:5]
	s_waitcnt lgkmcnt(0)
	s_barrier
	s_getreg_b32 s2, hwreg(HW_REG_XCC_ID, 0, 4)
	s_and_b32 s2, s2, 15
	v_cmp_eq_u32_e32 vcc, 0, v129
	v_writelane_b32 v251, s2, 5
	s_and_saveexec_b64 s[4:5], vcc
	s_cbranch_execz .LBB0_6
	s_mov_b64 s[6:7], exec
	v_mbcnt_lo_u32_b32 v1, s6, 0
	v_mbcnt_hi_u32_b32 v1, s7, v1
	v_cmp_eq_u32_e32 vcc, 0, v1
	s_and_b64 s[2:3], exec, vcc
	s_mov_b64 exec, s[2:3]
	s_cbranch_execz .LBB0_6
	v_readlane_b32 s2, v251, 5
	s_lshl_b32 s2, s2, 8
	s_bcnt1_i32_b64 s3, s[6:7]
	v_mov_b32_e32 v1, s2
	v_mov_b32_e32 v2, s3
	v_readlane_b32 s2, v251, 3
	v_readlane_b32 s3, v251, 4
	s_nop 4
	global_atomic_add v1, v2, s[2:3] offset:1024
